# grid barrier: 4 staggered polls in flight (was 2)
# baseline (speedup 1.0000x reference)
.Lsm0_prime:
	global_load_dword v252, v2, s[60:61] sc1
	s_sleep 6
	global_load_dword v253, v2, s[60:61] sc1
	s_sleep 6
	global_load_dword v254, v2, s[60:61] sc1
	s_sleep 6
	global_load_dword v255, v2, s[60:61] sc1
.Lsm0_loop:
	s_waitcnt vmcnt(3)
	v_readfirstlane_b32 s2, v252
	s_nop 3
	s_cmp_ge_u32 s2, s9
	s_cbranch_scc1 .Lsm0_done
	global_load_dword v252, v2, s[60:61] sc1
	s_waitcnt vmcnt(3)
	v_readfirstlane_b32 s2, v253
	s_nop 3
	s_cmp_ge_u32 s2, s9
	s_cbranch_scc1 .Lsm0_done
	global_load_dword v253, v2, s[60:61] sc1
	s_waitcnt vmcnt(3)
	v_readfirstlane_b32 s2, v254
	s_nop 3
	s_cmp_ge_u32 s2, s9
	s_cbranch_scc1 .Lsm0_done
	global_load_dword v254, v2, s[60:61] sc1
	s_waitcnt vmcnt(3)
	v_readfirstlane_b32 s2, v255
	s_nop 3
	s_cmp_ge_u32 s2, s9
	s_cbranch_scc1 .Lsm0_done
	global_load_dword v255, v2, s[60:61] sc1
	s_add_i32 s10, s10, 1
	s_and_b32 s2, s10, 63
	s_cmp_lg_u32 s2, 0
	s_cbranch_scc1 .Lsm0_loop
	v_mov_b32_e32 v6, 0x200
	global_load_dword v255, v6, s[60:61] sc1
	s_waitcnt vmcnt(0)
	v_readfirstlane_b32 s2, v255
	s_nop 3
	s_cmp_lg_u32 s2, 0
	s_cbranch_scc1 .Lsm0_done
	s_cmp_lt_u32 s10, 0x10000
	s_cbranch_scc1 .Lsm0_prime
	global_atomic_add v6, v4, s[60:61]
	s_waitcnt vmcnt(0)

.Lsm1_loop:
	s_waitcnt vmcnt(3)
	v_readfirstlane_b32 s2, v252
	s_nop 3
	s_cmp_ge_u32 s2, s7
	s_cbranch_scc1 .Lsm1_done
	global_load_dword v252, v2, s[60:61] sc1
	s_waitcnt vmcnt(3)
	v_readfirstlane_b32 s2, v253
	s_nop 3
	s_cmp_ge_u32 s2, s7
	s_cbranch_scc1 .Lsm1_done
	global_load_dword v253, v2, s[60:61] sc1
	s_waitcnt vmcnt(3)
	v_readfirstlane_b32 s2, v254
	s_nop 3
	s_cmp_ge_u32 s2, s7
	s_cbranch_scc1 .Lsm1_done
	global_load_dword v254, v2, s[60:61] sc1
	s_waitcnt vmcnt(3)
	v_readfirstlane_b32 s2, v255
	s_nop 3
	s_cmp_ge_u32 s2, s7
	s_cbranch_scc1 .Lsm1_done
	global_load_dword v255, v2, s[60:61] sc1
	s_add_i32 s8, s8, 1
	s_and_b32 s2, s8, 63
	s_cmp_lg_u32 s2, 0
	s_cbranch_scc1 .Lsm1_loop
	v_mov_b32_e32 v6, 0x200
	global_load_dword v255, v6, s[60:61] sc1
	s_waitcnt vmcnt(0)
	v_readfirstlane_b32 s2, v255
	s_nop 3
	s_cmp_lg_u32 s2, 0
	s_cbranch_scc1 .Lsm1_done
	s_cmp_lt_u32 s8, 0x10000
	s_cbranch_scc1 .Lsm1_prime
	global_atomic_add v6, v4, s[60:61]
	s_waitcnt vmcnt(0)

.Lsm3_prime:
	global_load_dword v252, v3, s[60:61] sc1
	s_sleep 6
	global_load_dword v253, v3, s[60:61] sc1
	s_sleep 6
	global_load_dword v254, v3, s[60:61] sc1
	s_sleep 6
	global_load_dword v255, v3, s[60:61] sc1
.Lsm3_loop:
	s_waitcnt vmcnt(3)
	v_readfirstlane_b32 s2, v252
	s_nop 3
	s_cmp_ge_u32 s2, s7
	s_cbranch_scc1 .Lsm3_done
	global_load_dword v252, v3, s[60:61] sc1
	s_waitcnt vmcnt(3)
	v_readfirstlane_b32 s2, v253
	s_nop 3
	s_cmp_ge_u32 s2, s7
	s_cbranch_scc1 .Lsm3_done
	global_load_dword v253, v3, s[60:61] sc1
	s_waitcnt vmcnt(3)
	v_readfirstlane_b32 s2, v254
	s_nop 3
	s_cmp_ge_u32 s2, s7
	s_cbranch_scc1 .Lsm3_done
	global_load_dword v254, v3, s[60:61] sc1
	s_waitcnt vmcnt(3)
	v_readfirstlane_b32 s2, v255
	s_nop 3
	s_cmp_ge_u32 s2, s7
	s_cbranch_scc1 .Lsm3_done
	global_load_dword v255, v3, s[60:61] sc1
	s_add_i32 s8, s8, 1
	s_and_b32 s2, s8, 63
	s_cmp_lg_u32 s2, 0
	s_cbranch_scc1 .Lsm3_loop
	v_mov_b32_e32 v7, 0x200
	global_load_dword v255, v7, s[60:61] sc1
	s_waitcnt vmcnt(0)
	v_readfirstlane_b32 s2, v255
	s_nop 3
	s_cmp_lg_u32 s2, 0
	s_cbranch_scc1 .Lsm3_done
	s_cmp_lt_u32 s8, 0x10000
	s_cbranch_scc1 .Lsm3_prime
	global_atomic_add v7, v5, s[60:61]
	s_waitcnt vmcnt(0)

.Lsm4_loop:
	s_waitcnt vmcnt(3)
	v_readfirstlane_b32 s2, v252
	s_nop 3
	s_cmp_ge_u32 s2, s5
	s_cbranch_scc1 .Lsm4_done
	global_load_dword v252, v3, s[60:61] sc1
	s_waitcnt vmcnt(3)
	v_readfirstlane_b32 s2, v253
	s_nop 3
	s_cmp_ge_u32 s2, s5
	s_cbranch_scc1 .Lsm4_done
	global_load_dword v253, v3, s[60:61] sc1
	s_waitcnt vmcnt(3)
	v_readfirstlane_b32 s2, v254
	s_nop 3
	s_cmp_ge_u32 s2, s5
	s_cbranch_scc1 .Lsm4_done
	global_load_dword v254, v3, s[60:61] sc1
	s_waitcnt vmcnt(3)
	v_readfirstlane_b32 s2, v255
	s_nop 3
	s_cmp_ge_u32 s2, s5
	s_cbranch_scc1 .Lsm4_done
	global_load_dword v255, v3, s[60:61] sc1
	s_add_i32 s6, s6, 1
	s_and_b32 s2, s6, 63
	s_cmp_lg_u32 s2, 0
	s_cbranch_scc1 .Lsm4_loop
	v_mov_b32_e32 v7, 0x200
	global_load_dword v255, v7, s[60:61] sc1
	s_waitcnt vmcnt(0)
	v_readfirstlane_b32 s2, v255
	s_nop 3
	s_cmp_lg_u32 s2, 0
	s_cbranch_scc1 .Lsm4_done
	s_cmp_lt_u32 s6, 0x10000
	s_cbranch_scc1 .Lsm4_prime
	global_atomic_add v7, v5, s[60:61]
	s_waitcnt vmcnt(0)

.Lsm5_loop:
	s_waitcnt vmcnt(3)
	v_readfirstlane_b32 s2, v252
	s_nop 3
	s_cmp_ge_u32 s2, s9
	s_cbranch_scc1 .Lsm5_done
	global_load_dword v252, v3, s[60:61] sc1
	s_waitcnt vmcnt(3)
	v_readfirstlane_b32 s2, v253
	s_nop 3
	s_cmp_ge_u32 s2, s9
	s_cbranch_scc1 .Lsm5_done
	global_load_dword v253, v3, s[60:61] sc1
	s_waitcnt vmcnt(3)
	v_readfirstlane_b32 s2, v254
	s_nop 3
	s_cmp_ge_u32 s2, s9
	s_cbranch_scc1 .Lsm5_done
	global_load_dword v254, v3, s[60:61] sc1
	s_waitcnt vmcnt(3)
	v_readfirstlane_b32 s2, v255
	s_nop 3
	s_cmp_ge_u32 s2, s9
	s_cbranch_scc1 .Lsm5_done
	global_load_dword v255, v3, s[60:61] sc1
	s_add_i32 s10, s10, 1
	s_and_b32 s2, s10, 63
	s_cmp_lg_u32 s2, 0
	s_cbranch_scc1 .Lsm5_loop
	v_mov_b32_e32 v7, 0x200
	global_load_dword v255, v7, s[60:61] sc1
	s_waitcnt vmcnt(0)
	v_readfirstlane_b32 s2, v255
	s_nop 3
	s_cmp_lg_u32 s2, 0
	s_cbranch_scc1 .Lsm5_done
	s_cmp_lt_u32 s10, 0x10000
	s_cbranch_scc1 .Lsm5_prime
	global_atomic_add v7, v5, s[60:61]
	s_waitcnt vmcnt(0)
